# phase-3 prompt strip rewritten by hand: v^T fragments and decay rows of 8-chunk batches through LDS (3 LDS-DMA pieces per wave and batch, one barrier per batch), k fragments 3 chunks ahead in a regist
# speedup vs baseline: 1.0102x; 1.0018x over previous
; __device__ __forceinline__ int tid_of_(int wave) { return wave * 64 + lane_id_(); }
; template <int NDV>
; __device__ __forceinline__ void ph_g12_strip(Frame& F, int id) {
;     int tid_ = tid_of_(F.wave); asm volatile("" : "+v"(tid_)); const int lane = tid_ & 63, fr = lane & 15, fq = lane >> 4, w = F.wave;
;     const unsigned l16 = (unsigned)lane * 16u;
;     const unsigned sto = (unsigned)(((fq >> 1) * 16 + fr) * 16 + (fq & 1) * 8);
;     constexpr int PH = 32 / NDV;
;     const int seq = id / (NH * PH), h = (id / PH) % NH, sl = id % PH;
;     const int ci0 = seq * 128;
;     const unsigned char* vb0 = F.ws + WS_VT + (((size_t)ci0 * 128 + h * 32 + NDV * sl) * 2) * 1024;
;     const unsigned char* kb0 = F.ws + WS_KINT + (((size_t)ci0 * 64 + h * 16 + 2 * w) * 2) * 1024;
;     const float* Ap0 = (const float*)(F.ws + WS_AOUT) + (size_t)ci0 * GK + h * DK + 32 * w + 4 * fq;
; __global__ void __launch_bounds__(NTHR, 2) fwd_kernel(Args args) {
;     ...
;         for (int id = F.vcu; id < 256 + 128; id += F.G) { if (id < 256) ph_g12_strip<1>(F, id); else ph_g1(F, NCHK_P * NH, id - 256, 128); }
.LBB0_471:
.LBB0_472:
	v_readlane_b32 s8, v255, 41
	s_and_b32 s1, s94, 0xffffffc0
	s_lshl_b32 s3, s8, 2
	s_add_u32 s44, s34, 0x4d400000
	s_addc_u32 s45, s35, 0
	s_add_u32 s46, s34, 0x51c00000
	s_addc_u32 s47, s35, 0
	s_add_u32 s6, s34, 0x8100000
	s_addc_u32 s7, s35, 0
	s_add_u32 s48, s34, 0x47c00000
	s_addc_u32 s49, s35, 0
	s_lshl_b32 s0, s8, 11
	s_lshl_b32 s50, s8, 1
	s_lshl_b32 s10, s8, 5
	s_and_b32 s51, s8, 0x3fffffe
	s_bfe_u32 s62, s94, 0x10006
	s_add_u32 s12, s34, 0x3d400000
	s_addc_u32 s13, s35, 0
	s_add_u32 s14, s34, 0x100000
	s_addc_u32 s15, s35, 0
	s_add_u32 s63, s70, 0x12000000
	v_mbcnt_hi_u32_b32 v166, -1, v254
	s_addc_u32 s64, s71, 0
	v_add_u32_e32 v172, s1, v166
	s_ashr_i32 s1, s0, 31
	s_mov_b32 s9, 0
	s_lshl_b64 s[16:17], s[0:1], 4
	v_readlane_b32 s78, v255, 2
	s_lshl_b64 s[0:1], s[94:95], 1
	s_mov_b32 s11, s9
	s_or_b32 s65, s10, 16
	s_add_i32 s66, s78, 0x300
	s_and_b32 s67, s1, 1
	s_and_b32 s72, s0, 0xffffff80
	v_mov_b32_e32 v145, 0
	s_movk_i32 s73, 0x1000
	s_mov_b64 s[18:19], 0x40000
	s_mov_b32 s74, 0x40000
	s_mov_b64 s[20:21], 0x80000
	s_movk_i32 s75, 0x3000
	s_mov_b64 s[24:25], 0xc0000
	s_mov_b32 s76, 0xc0000
	s_mov_b64 s[26:27], 0x4000
	s_mov_b32 s77, s78
	s_branch .LBB0_475
.LBB0_474:
	s_add_i32 s78, s33, s78
	s_add_i32 s77, s77, s33
	s_add_i32 s66, s66, s33
	s_cmpk_gt_i32 s78, 0x17f
	s_cbranch_scc1 .LBB0_513

; __device__ __forceinline__ int tid_of_(int wave) { return wave * 64 + lane_id_(); }
; template <int NDV>
; __device__ __forceinline__ void ph_g12_strip(Frame& F, int id) {
;     int tid_ = tid_of_(F.wave); asm volatile("" : "+v"(tid_)); const int lane = tid_ & 63, fr = lane & 15, fq = lane >> 4, w = F.wave;
;     const unsigned l16 = (unsigned)lane * 16u;
;     const unsigned sto = (unsigned)(((fq >> 1) * 16 + fr) * 16 + (fq & 1) * 8);
;     constexpr int PH = 32 / NDV;
;     const int seq = id / (NH * PH), h = (id / PH) % NH, sl = id % PH;
;     const int ci0 = seq * 128;
;     const unsigned char* vb0 = F.ws + WS_VT + (((size_t)ci0 * 128 + h * 32 + NDV * sl) * 2) * 1024;
;     const unsigned char* kb0 = F.ws + WS_KINT + (((size_t)ci0 * 64 + h * 16 + 2 * w) * 2) * 1024;
;     const float* Ap0 = (const float*)(F.ws + WS_AOUT) + (size_t)ci0 * GK + h * DK + 32 * w + 4 * fq;
;     f32x4 S[2][NDV];
; #pragma unroll
;     for (int j = 0; j < 2; ++j)
; #pragma unroll
;         for (int n = 0; n < NDV; ++n) S[j][n] = (f32x4){0.f, 0.f, 0.f, 0.f};
;     bf16x8 rk[4][2][2], rv[4][NDV][2]; f32x4 rA[4][2];
;     ...
;     G12_LOAD(0, 0); G12_LOAD(1, 1); G12_LOAD(2, 2); G12_LOAD(3, 3);
; #pragma unroll 1
;     for (int c0 = 0; c0 < 128; c0 += 4) {
; #pragma unroll
;         for (int u = 0; u < 4; ++u) {
;             const int cc = c0 + u;
;             unsigned char* slot = (unsigned char*)slot_ptr(F, ci0 + cc, h);
;             f32x4 D[2][NDV];
; #pragma unroll
;             for (int j = 0; j < 2; ++j)
; #pragma unroll
;                 for (int n = 0; n < NDV; ++n) { D[j][n] = (f32x4){0.f, 0.f, 0.f, 0.f};
; #pragma unroll
;                     for (int ks = 0; ks < 2; ++ks) D[j][n] = __builtin_amdgcn_mfma_f32_16x16x32_bf16(rk[u][j][ks], rv[u][n][ks], D[j][n], 0, 0, 0); }
; #pragma unroll
;             for (int j = 0; j < 2; ++j) { const int t = 2 * w + j, qd = t >> 2, c = t & 3; const f32x4 A = rA[u][j];
; #pragma unroll
;                 for (int n = 0; n < NDV; ++n) { const int nn = NDV * sl + n; v2u o; o.x = pk2(S[j][n][0], S[j][n][1]); o.y = pk2(S[j][n][2], S[j][n][3]);
;                     *(v2u*)(slot + (size_t)((nn * 8 + 2 * qd + (c >> 1)) * 64 + 2 * (c & 1) * 16) * 16 + sto) = o;
;                     S[j][n] = (S[j][n] + D[j][n]) * A; } }
;             if (cc + 4 < 128) G12_LOAD(u, cc + 4);
.LBB0_479:
	s_and_b64 vcc, exec, s[0:1]
	s_cbranch_vccz .LBB0_474
	v_readlane_b32 s79, v255, 41
	s_lshr_b32 s58, s78, 7
	s_bfe_u32 s59, s78, 0x20005
	s_and_b32 s60, s78, 31
	v_and_b32_e32 v116, 15, v166
	v_lshrrev_b32_e32 v117, 4, v166
	v_lshlrev_b32_e32 v248, 4, v166
	s_lshl_b32 s0, s79, 7
	v_lshl_add_u32 v249, v117, 4, s0
	v_lshrrev_b32_e32 v118, 1, v117
	v_and_b32_e32 v119, 1, v117
	v_lshlrev_b32_e32 v251, 8, v118
	v_lshl_add_u32 v251, v116, 4, v251
	v_lshl_add_u32 v251, v119, 3, v251
	s_lshl_b32 s0, s58, 24
	s_lshl_b32 s1, s59, 15
	s_add_u32 s0, s0, s1
	s_lshl_b32 s1, s79, 12
	s_add_u32 s0, s0, s1
	s_add_u32 s0, s0, 0x51c00000
	s_add_u32 s28, s34, s0
	s_addc_u32 s29, s35, 0
	s_mov_b32 s0, 0x100000
	s_mov_b32 s1, 0x3d400000
	s_cmp_lg_u32 s58, 0
	s_cselect_b32 s0, s1, s0
	s_lshl_b32 s1, s59, 18
	s_add_u32 s0, s0, s1
	s_lshl_b32 s1, s60, 13
	s_add_u32 s0, s0, s1
	s_lshl_b32 s1, s79, 10
	s_add_u32 s0, s0, s1
	s_add_u32 s40, s34, s0
	s_addc_u32 s41, s35, 0
	s_lshl_b32 s0, s58, 25
	s_lshl_b32 s1, s59, 16
	s_add_u32 s0, s0, s1
	s_lshl_b32 s1, s60, 11
	s_add_u32 s0, s0, s1
	s_add_u32 s80, s0, 0x4d400000
	s_lshl_b32 s0, s58, 19
	s_lshl_b32 s1, s59, 10
	s_add_u32 s0, s0, s1
	s_add_u32 s81, s0, 0x47c00000
	s_mul_i32 s82, s79, 3
	s_add_i32 s0, s82, 0
	s_cmp_lt_u32 s0, 16
	s_cbranch_scc0 .Lstrip2_a0
	s_lshr_b32 s1, s0, 1
	s_lshl_b32 s1, s1, 18
	s_and_b32 s42, s0, 1
	s_lshl_b32 s42, s42, 10
	s_add_u32 s1, s1, s42
	s_add_u32 s30, s80, s1
	s_mov_b32 s37, 0x200000
	s_lshl_b32 s42, s0, 10
	s_branch .Lstrip2_d0
.Lstrip2_a0:
	s_sub_u32 s0, s0, 16
	s_lshl_b32 s1, s0, 12
	s_add_u32 s30, s81, s1
	s_mov_b32 s37, 0x8000
	s_lshl_b32 s42, s0, 10
	s_add_u32 s42, s42, 0x4000
.Lstrip2_d0:
	s_add_i32 s0, s82, 1
	s_cmp_lt_u32 s0, 16
	s_cbranch_scc0 .Lstrip2_a1
	s_lshr_b32 s1, s0, 1
	s_lshl_b32 s1, s1, 18
	s_and_b32 s43, s0, 1
	s_lshl_b32 s43, s43, 10
	s_add_u32 s1, s1, s43
	s_add_u32 s31, s80, s1
	s_mov_b32 s38, 0x200000
	s_lshl_b32 s43, s0, 10
	s_branch .Lstrip2_d1
.Lstrip2_a1:
	s_sub_u32 s0, s0, 16
	s_lshl_b32 s1, s0, 12
	s_add_u32 s31, s81, s1
	s_mov_b32 s38, 0x8000
	s_lshl_b32 s43, s0, 10
	s_add_u32 s43, s43, 0x4000
.Lstrip2_d1:
	s_add_i32 s0, s82, 2
	s_cmp_lt_u32 s0, 16
	s_cbranch_scc0 .Lstrip2_a2
	s_lshr_b32 s1, s0, 1
	s_lshl_b32 s1, s1, 18
	s_and_b32 s61, s0, 1
	s_lshl_b32 s61, s61, 10
	s_add_u32 s1, s1, s61
	s_add_u32 s36, s80, s1
	s_mov_b32 s39, 0x200000
	s_lshl_b32 s61, s0, 10
	s_branch .Lstrip2_d2
.Lstrip2_a2:
	s_sub_u32 s0, s0, 16
	s_lshl_b32 s1, s0, 12
	s_add_u32 s36, s81, s1
	s_mov_b32 s39, 0x8000
	s_lshl_b32 s61, s0, 10
	s_add_u32 s61, s61, 0x4000
.Lstrip2_d2:
	v_mov_b32_e32 v0, 0
	v_mov_b32_e32 v1, 0
	v_mov_b32_e32 v2, 0
	v_mov_b32_e32 v3, 0
	v_mov_b32_e32 v4, 0
	v_mov_b32_e32 v5, 0
	v_mov_b32_e32 v6, 0
	v_mov_b32_e32 v7, 0
	v_add_u32_e32 v116, s30, v248
	s_add_i32 m0, s42, 0x0
	s_add_u32 s30, s30, s37
	global_load_lds_dwordx4 v116, s[34:35]
	v_add_u32_e32 v116, s31, v248
	s_add_i32 m0, s43, 0x0
	s_add_u32 s31, s31, s38
	global_load_lds_dwordx4 v116, s[34:35]
	v_add_u32_e32 v116, s36, v248
	s_add_i32 m0, s61, 0x0
	s_add_u32 s36, s36, s39
	global_load_lds_dwordx4 v116, s[34:35]
	global_load_dwordx4 v[16:19], v248, s[28:29]
	global_load_dwordx4 v[20:23], v248, s[28:29] offset:1024
	global_load_dwordx4 v[24:27], v248, s[28:29] offset:2048
	global_load_dwordx4 v[28:31], v248, s[28:29] offset:3072
	s_add_u32 s28, s28, 0x20000
	s_addc_u32 s29, s29, 0
	global_load_dwordx4 v[32:35], v248, s[28:29]
	global_load_dwordx4 v[36:39], v248, s[28:29] offset:1024
	global_load_dwordx4 v[40:43], v248, s[28:29] offset:2048
	global_load_dwordx4 v[44:47], v248, s[28:29] offset:3072
	s_add_u32 s28, s28, 0x20000
	s_addc_u32 s29, s29, 0
	global_load_dwordx4 v[48:51], v248, s[28:29]
	global_load_dwordx4 v[52:55], v248, s[28:29] offset:1024
	global_load_dwordx4 v[56:59], v248, s[28:29] offset:2048
	global_load_dwordx4 v[60:63], v248, s[28:29] offset:3072
	s_add_u32 s28, s28, 0x20000
	s_addc_u32 s29, s29, 0
	s_movk_i32 s8, 8
	s_waitcnt vmcnt(0)
.Lstrip2_loop:
	s_barrier
	v_add_u32_e32 v116, s30, v248
	s_add_i32 m0, s42, 0x6000
	s_add_u32 s30, s30, s37
	global_load_lds_dwordx4 v116, s[34:35]
	v_add_u32_e32 v116, s31, v248
	s_add_i32 m0, s43, 0x6000
	s_add_u32 s31, s31, s38
	global_load_lds_dwordx4 v116, s[34:35]
	v_add_u32_e32 v116, s36, v248
	s_add_i32 m0, s61, 0x6000
	s_add_u32 s36, s36, s39
	global_load_lds_dwordx4 v116, s[34:35]
	ds_read_b128 v[80:83], v248 offset:0
	ds_read_b128 v[84:87], v248 offset:1024
	ds_read_b128 v[88:91], v249 offset:16384
	ds_read_b128 v[92:95], v249 offset:16448
	global_load_dwordx4 v[64:67], v248, s[28:29]
	global_load_dwordx4 v[68:71], v248, s[28:29] offset:1024
	global_load_dwordx4 v[72:75], v248, s[28:29] offset:2048
	global_load_dwordx4 v[76:79], v248, s[28:29] offset:3072
	s_add_u32 s28, s28, 0x20000
	s_addc_u32 s29, s29, 0
	ds_read_b128 v[96:99], v248 offset:2048
	ds_read_b128 v[100:103], v248 offset:3072
	ds_read_b128 v[104:107], v249 offset:17408
	ds_read_b128 v[108:111], v249 offset:17472
	s_waitcnt vmcnt(21)
	s_waitcnt lgkmcnt(4)
; __device__ __forceinline__ unsigned pk2(float lo, float hi) { return pg8::cvt_pk_bf16(lo, hi); }
; template <int NDV>
; __device__ __forceinline__ void ph_g12_strip(Frame& F, int id) {
;     ...
;     for (int c0 = 0; c0 < 128; c0 += 4) {
; #pragma unroll
;         for (int u = 0; u < 4; ++u) {
;             const int cc = c0 + u;
;             unsigned char* slot = (unsigned char*)slot_ptr(F, ci0 + cc, h);
;             f32x4 D[2][NDV];
; #pragma unroll
;             for (int j = 0; j < 2; ++j)
; #pragma unroll
;                 for (int n = 0; n < NDV; ++n) { D[j][n] = (f32x4){0.f, 0.f, 0.f, 0.f};
; #pragma unroll
;                     for (int ks = 0; ks < 2; ++ks) D[j][n] = __builtin_amdgcn_mfma_f32_16x16x32_bf16(rk[u][j][ks], rv[u][n][ks], D[j][n], 0, 0, 0); }
; #pragma unroll
;             for (int j = 0; j < 2; ++j) { const int t = 2 * w + j, qd = t >> 2, c = t & 3; const f32x4 A = rA[u][j];
; #pragma unroll
;                 for (int n = 0; n < NDV; ++n) { const int nn = NDV * sl + n; v2u o; o.x = pk2(S[j][n][0], S[j][n][1]); o.y = pk2(S[j][n][2], S[j][n][3]);
;                     *(v2u*)(slot + (size_t)((nn * 8 + 2 * qd + (c >> 1)) * 64 + 2 * (c & 1) * 16) * 16 + sto) = o;
;                     S[j][n] = (S[j][n] + D[j][n]) * A; } }
;             if (cc + 4 < 128) G12_LOAD(u, cc + 4);
	v_mfma_f32_16x16x32_bf16 v[8:11], v[16:19], v[80:83], 0
	v_mfma_f32_16x16x32_bf16 v[12:15], v[24:27], v[80:83], 0
	v_mfma_f32_16x16x32_bf16 v[8:11], v[20:23], v[84:87], v[8:11]
	v_mfma_f32_16x16x32_bf16 v[12:15], v[28:31], v[84:87], v[12:15]
	v_cvt_pk_bf16_f32 v112, v0, v1
	v_cvt_pk_bf16_f32 v113, v2, v3
	v_cvt_pk_bf16_f32 v114, v4, v5
	v_cvt_pk_bf16_f32 v115, v6, v7
	global_store_dwordx2 v251, v[112:113], s[40:41]
	global_store_dwordx2 v251, v[114:115], s[40:41] offset:512
	s_add_u32 s40, s40, 0x100000
	s_addc_u32 s41, s41, 0
	s_nop 7
	v_add_f32_e32 v0, v0, v8
	v_add_f32_e32 v1, v1, v9
	v_add_f32_e32 v2, v2, v10
	v_add_f32_e32 v3, v3, v11
	v_add_f32_e32 v4, v4, v12
	v_add_f32_e32 v5, v5, v13
	v_add_f32_e32 v6, v6, v14
	v_add_f32_e32 v7, v7, v15
	v_mul_f32_e32 v0, v0, v88
	v_mul_f32_e32 v1, v1, v89
	v_mul_f32_e32 v2, v2, v90
	v_mul_f32_e32 v3, v3, v91
	v_mul_f32_e32 v4, v4, v92
	v_mul_f32_e32 v5, v5, v93
	v_mul_f32_e32 v6, v6, v94
	v_mul_f32_e32 v7, v7, v95
	global_load_dwordx4 v[16:19], v248, s[28:29]
	global_load_dwordx4 v[20:23], v248, s[28:29] offset:1024
	global_load_dwordx4 v[24:27], v248, s[28:29] offset:2048
	global_load_dwordx4 v[28:31], v248, s[28:29] offset:3072
	s_add_u32 s28, s28, 0x20000
	s_addc_u32 s29, s29, 0
	ds_read_b128 v[80:83], v248 offset:4096
	ds_read_b128 v[84:87], v248 offset:5120
	ds_read_b128 v[88:91], v249 offset:18432
	ds_read_b128 v[92:95], v249 offset:18496
	s_waitcnt vmcnt(21)
	s_waitcnt lgkmcnt(4)
	v_mfma_f32_16x16x32_bf16 v[8:11], v[32:35], v[96:99], 0
	v_mfma_f32_16x16x32_bf16 v[12:15], v[40:43], v[96:99], 0
	v_mfma_f32_16x16x32_bf16 v[8:11], v[36:39], v[100:103], v[8:11]
	v_mfma_f32_16x16x32_bf16 v[12:15], v[44:47], v[100:103], v[12:15]
	v_cvt_pk_bf16_f32 v112, v0, v1
	v_cvt_pk_bf16_f32 v113, v2, v3
	v_cvt_pk_bf16_f32 v114, v4, v5
	v_cvt_pk_bf16_f32 v115, v6, v7
	global_store_dwordx2 v251, v[112:113], s[40:41]
	global_store_dwordx2 v251, v[114:115], s[40:41] offset:512
	s_add_u32 s40, s40, 0x100000
	s_addc_u32 s41, s41, 0
	s_nop 7
	v_add_f32_e32 v0, v0, v8
	v_add_f32_e32 v1, v1, v9
	v_add_f32_e32 v2, v2, v10
	v_add_f32_e32 v3, v3, v11
	v_add_f32_e32 v4, v4, v12
	v_add_f32_e32 v5, v5, v13
	v_add_f32_e32 v6, v6, v14
	v_add_f32_e32 v7, v7, v15
	v_mul_f32_e32 v0, v0, v104
	v_mul_f32_e32 v1, v1, v105
	v_mul_f32_e32 v2, v2, v106
	v_mul_f32_e32 v3, v3, v107
	v_mul_f32_e32 v4, v4, v108
	v_mul_f32_e32 v5, v5, v109
	v_mul_f32_e32 v6, v6, v110
	v_mul_f32_e32 v7, v7, v111
	global_load_dwordx4 v[32:35], v248, s[28:29]
	global_load_dwordx4 v[36:39], v248, s[28:29] offset:1024
	global_load_dwordx4 v[40:43], v248, s[28:29] offset:2048
	global_load_dwordx4 v[44:47], v248, s[28:29] offset:3072
	s_add_u32 s28, s28, 0x20000
	s_addc_u32 s29, s29, 0
	ds_read_b128 v[96:99], v248 offset:6144
	ds_read_b128 v[100:103], v248 offset:7168
	ds_read_b128 v[104:107], v249 offset:19456
	ds_read_b128 v[108:111], v249 offset:19520
	s_waitcnt vmcnt(21)
	s_waitcnt lgkmcnt(4)
	v_mfma_f32_16x16x32_bf16 v[8:11], v[48:51], v[80:83], 0
	v_mfma_f32_16x16x32_bf16 v[12:15], v[56:59], v[80:83], 0
	v_mfma_f32_16x16x32_bf16 v[8:11], v[52:55], v[84:87], v[8:11]
	v_mfma_f32_16x16x32_bf16 v[12:15], v[60:63], v[84:87], v[12:15]
	v_cvt_pk_bf16_f32 v112, v0, v1
	v_cvt_pk_bf16_f32 v113, v2, v3
	v_cvt_pk_bf16_f32 v114, v4, v5
	v_cvt_pk_bf16_f32 v115, v6, v7
	global_store_dwordx2 v251, v[112:113], s[40:41]
	global_store_dwordx2 v251, v[114:115], s[40:41] offset:512
	s_add_u32 s40, s40, 0x100000
	s_addc_u32 s41, s41, 0
	s_nop 7
	v_add_f32_e32 v0, v0, v8
	v_add_f32_e32 v1, v1, v9
	v_add_f32_e32 v2, v2, v10
	v_add_f32_e32 v3, v3, v11
	v_add_f32_e32 v4, v4, v12
	v_add_f32_e32 v5, v5, v13
	v_add_f32_e32 v6, v6, v14
	v_add_f32_e32 v7, v7, v15
	v_mul_f32_e32 v0, v0, v88
	v_mul_f32_e32 v1, v1, v89
	v_mul_f32_e32 v2, v2, v90
	v_mul_f32_e32 v3, v3, v91
	v_mul_f32_e32 v4, v4, v92
	v_mul_f32_e32 v5, v5, v93
	v_mul_f32_e32 v6, v6, v94
	v_mul_f32_e32 v7, v7, v95
	global_load_dwordx4 v[48:51], v248, s[28:29]
	global_load_dwordx4 v[52:55], v248, s[28:29] offset:1024
	global_load_dwordx4 v[56:59], v248, s[28:29] offset:2048
	global_load_dwordx4 v[60:63], v248, s[28:29] offset:3072
	s_add_u32 s28, s28, 0x20000
	s_addc_u32 s29, s29, 0
	ds_read_b128 v[80:83], v248 offset:8192
	ds_read_b128 v[84:87], v248 offset:9216
	ds_read_b128 v[88:91], v249 offset:20480
	ds_read_b128 v[92:95], v249 offset:20544
	s_waitcnt vmcnt(18)
	s_waitcnt lgkmcnt(4)
	v_mfma_f32_16x16x32_bf16 v[8:11], v[64:67], v[96:99], 0
	v_mfma_f32_16x16x32_bf16 v[12:15], v[72:75], v[96:99], 0
	v_mfma_f32_16x16x32_bf16 v[8:11], v[68:71], v[100:103], v[8:11]
	v_mfma_f32_16x16x32_bf16 v[12:15], v[76:79], v[100:103], v[12:15]
	v_cvt_pk_bf16_f32 v112, v0, v1
	v_cvt_pk_bf16_f32 v113, v2, v3
	v_cvt_pk_bf16_f32 v114, v4, v5
	v_cvt_pk_bf16_f32 v115, v6, v7
	global_store_dwordx2 v251, v[112:113], s[40:41]
	global_store_dwordx2 v251, v[114:115], s[40:41] offset:512
	s_add_u32 s40, s40, 0x100000
	s_addc_u32 s41, s41, 0
	s_nop 7
	v_add_f32_e32 v0, v0, v8
	v_add_f32_e32 v1, v1, v9
	v_add_f32_e32 v2, v2, v10
	v_add_f32_e32 v3, v3, v11
	v_add_f32_e32 v4, v4, v12
	v_add_f32_e32 v5, v5, v13
	v_add_f32_e32 v6, v6, v14
	v_add_f32_e32 v7, v7, v15
	v_mul_f32_e32 v0, v0, v104
	v_mul_f32_e32 v1, v1, v105
	v_mul_f32_e32 v2, v2, v106
	v_mul_f32_e32 v3, v3, v107
	v_mul_f32_e32 v4, v4, v108
	v_mul_f32_e32 v5, v5, v109
	v_mul_f32_e32 v6, v6, v110
	v_mul_f32_e32 v7, v7, v111
	global_load_dwordx4 v[64:67], v248, s[28:29]
	global_load_dwordx4 v[68:71], v248, s[28:29] offset:1024
	global_load_dwordx4 v[72:75], v248, s[28:29] offset:2048
	global_load_dwordx4 v[76:79], v248, s[28:29] offset:3072
	s_add_u32 s28, s28, 0x20000
	s_addc_u32 s29, s29, 0
	ds_read_b128 v[96:99], v248 offset:10240
	ds_read_b128 v[100:103], v248 offset:11264
	ds_read_b128 v[104:107], v249 offset:21504
	ds_read_b128 v[108:111], v249 offset:21568
	s_waitcnt vmcnt(18)
; __device__ __forceinline__ unsigned pk2(float lo, float hi) { return pg8::cvt_pk_bf16(lo, hi); }
; template <int NDV>
; __device__ __forceinline__ void ph_g12_strip(Frame& F, int id) {
;     ...
;     for (int c0 = 0; c0 < 128; c0 += 4) {
; #pragma unroll
;         for (int u = 0; u < 4; ++u) {
;             const int cc = c0 + u;
;             unsigned char* slot = (unsigned char*)slot_ptr(F, ci0 + cc, h);
;             f32x4 D[2][NDV];
; #pragma unroll
;             for (int j = 0; j < 2; ++j)
; #pragma unroll
;                 for (int n = 0; n < NDV; ++n) { D[j][n] = (f32x4){0.f, 0.f, 0.f, 0.f};
; #pragma unroll
;                     for (int ks = 0; ks < 2; ++ks) D[j][n] = __builtin_amdgcn_mfma_f32_16x16x32_bf16(rk[u][j][ks], rv[u][n][ks], D[j][n], 0, 0, 0); }
; #pragma unroll
;             for (int j = 0; j < 2; ++j) { const int t = 2 * w + j, qd = t >> 2, c = t & 3; const f32x4 A = rA[u][j];
; #pragma unroll
;                 for (int n = 0; n < NDV; ++n) { const int nn = NDV * sl + n; v2u o; o.x = pk2(S[j][n][0], S[j][n][1]); o.y = pk2(S[j][n][2], S[j][n][3]);
;                     *(v2u*)(slot + (size_t)((nn * 8 + 2 * qd + (c >> 1)) * 64 + 2 * (c & 1) * 16) * 16 + sto) = o;
;                     S[j][n] = (S[j][n] + D[j][n]) * A; } }
;             if (cc + 4 < 128) G12_LOAD(u, cc + 4);
	s_waitcnt lgkmcnt(4)
	v_mfma_f32_16x16x32_bf16 v[8:11], v[16:19], v[80:83], 0
	v_mfma_f32_16x16x32_bf16 v[12:15], v[24:27], v[80:83], 0
	v_mfma_f32_16x16x32_bf16 v[8:11], v[20:23], v[84:87], v[8:11]
	v_mfma_f32_16x16x32_bf16 v[12:15], v[28:31], v[84:87], v[12:15]
	v_cvt_pk_bf16_f32 v112, v0, v1
	v_cvt_pk_bf16_f32 v113, v2, v3
	v_cvt_pk_bf16_f32 v114, v4, v5
	v_cvt_pk_bf16_f32 v115, v6, v7
	global_store_dwordx2 v251, v[112:113], s[40:41]
	global_store_dwordx2 v251, v[114:115], s[40:41] offset:512
	s_add_u32 s40, s40, 0x100000
	s_addc_u32 s41, s41, 0
	s_nop 7
	v_add_f32_e32 v0, v0, v8
	v_add_f32_e32 v1, v1, v9
	v_add_f32_e32 v2, v2, v10
	v_add_f32_e32 v3, v3, v11
	v_add_f32_e32 v4, v4, v12
	v_add_f32_e32 v5, v5, v13
	v_add_f32_e32 v6, v6, v14
	v_add_f32_e32 v7, v7, v15
	v_mul_f32_e32 v0, v0, v88
	v_mul_f32_e32 v1, v1, v89
	v_mul_f32_e32 v2, v2, v90
	v_mul_f32_e32 v3, v3, v91
	v_mul_f32_e32 v4, v4, v92
	v_mul_f32_e32 v5, v5, v93
	v_mul_f32_e32 v6, v6, v94
	v_mul_f32_e32 v7, v7, v95
	global_load_dwordx4 v[16:19], v248, s[28:29]
	global_load_dwordx4 v[20:23], v248, s[28:29] offset:1024
	global_load_dwordx4 v[24:27], v248, s[28:29] offset:2048
	global_load_dwordx4 v[28:31], v248, s[28:29] offset:3072
	s_add_u32 s28, s28, 0x20000
	s_addc_u32 s29, s29, 0
	ds_read_b128 v[80:83], v248 offset:12288
	ds_read_b128 v[84:87], v248 offset:13312
	ds_read_b128 v[88:91], v249 offset:22528
	ds_read_b128 v[92:95], v249 offset:22592
	s_waitcnt vmcnt(18)
	s_waitcnt lgkmcnt(4)
	v_mfma_f32_16x16x32_bf16 v[8:11], v[32:35], v[96:99], 0
	v_mfma_f32_16x16x32_bf16 v[12:15], v[40:43], v[96:99], 0
	v_mfma_f32_16x16x32_bf16 v[8:11], v[36:39], v[100:103], v[8:11]
	v_mfma_f32_16x16x32_bf16 v[12:15], v[44:47], v[100:103], v[12:15]
	v_cvt_pk_bf16_f32 v112, v0, v1
	v_cvt_pk_bf16_f32 v113, v2, v3
	v_cvt_pk_bf16_f32 v114, v4, v5
	v_cvt_pk_bf16_f32 v115, v6, v7
	global_store_dwordx2 v251, v[112:113], s[40:41]
	global_store_dwordx2 v251, v[114:115], s[40:41] offset:512
	s_add_u32 s40, s40, 0x100000
	s_addc_u32 s41, s41, 0
	s_nop 7
	v_add_f32_e32 v0, v0, v8
	v_add_f32_e32 v1, v1, v9
	v_add_f32_e32 v2, v2, v10
	v_add_f32_e32 v3, v3, v11
	v_add_f32_e32 v4, v4, v12
	v_add_f32_e32 v5, v5, v13
	v_add_f32_e32 v6, v6, v14
	v_add_f32_e32 v7, v7, v15
	v_mul_f32_e32 v0, v0, v104
	v_mul_f32_e32 v1, v1, v105
	v_mul_f32_e32 v2, v2, v106
	v_mul_f32_e32 v3, v3, v107
	v_mul_f32_e32 v4, v4, v108
	v_mul_f32_e32 v5, v5, v109
	v_mul_f32_e32 v6, v6, v110
	v_mul_f32_e32 v7, v7, v111
	global_load_dwordx4 v[32:35], v248, s[28:29]
	global_load_dwordx4 v[36:39], v248, s[28:29] offset:1024
	global_load_dwordx4 v[40:43], v248, s[28:29] offset:2048
	global_load_dwordx4 v[44:47], v248, s[28:29] offset:3072
	s_add_u32 s28, s28, 0x20000
	s_addc_u32 s29, s29, 0
	ds_read_b128 v[96:99], v248 offset:14336
	ds_read_b128 v[100:103], v248 offset:15360
	ds_read_b128 v[104:107], v249 offset:23552
	ds_read_b128 v[108:111], v249 offset:23616
	s_waitcnt vmcnt(18)
	s_waitcnt lgkmcnt(4)
	v_mfma_f32_16x16x32_bf16 v[8:11], v[48:51], v[80:83], 0
	v_mfma_f32_16x16x32_bf16 v[12:15], v[56:59], v[80:83], 0
	v_mfma_f32_16x16x32_bf16 v[8:11], v[52:55], v[84:87], v[8:11]
	v_mfma_f32_16x16x32_bf16 v[12:15], v[60:63], v[84:87], v[12:15]
	v_cvt_pk_bf16_f32 v112, v0, v1
	v_cvt_pk_bf16_f32 v113, v2, v3
	v_cvt_pk_bf16_f32 v114, v4, v5
	v_cvt_pk_bf16_f32 v115, v6, v7
	global_store_dwordx2 v251, v[112:113], s[40:41]
	global_store_dwordx2 v251, v[114:115], s[40:41] offset:512
	s_add_u32 s40, s40, 0x100000
	s_addc_u32 s41, s41, 0
	s_nop 7
	v_add_f32_e32 v0, v0, v8
	v_add_f32_e32 v1, v1, v9
	v_add_f32_e32 v2, v2, v10
	v_add_f32_e32 v3, v3, v11
	v_add_f32_e32 v4, v4, v12
	v_add_f32_e32 v5, v5, v13
	v_add_f32_e32 v6, v6, v14
	v_add_f32_e32 v7, v7, v15
	v_mul_f32_e32 v0, v0, v88
	v_mul_f32_e32 v1, v1, v89
	v_mul_f32_e32 v2, v2, v90
	v_mul_f32_e32 v3, v3, v91
	v_mul_f32_e32 v4, v4, v92
	v_mul_f32_e32 v5, v5, v93
	v_mul_f32_e32 v6, v6, v94
	v_mul_f32_e32 v7, v7, v95
	global_load_dwordx4 v[48:51], v248, s[28:29]
	global_load_dwordx4 v[52:55], v248, s[28:29] offset:1024
	global_load_dwordx4 v[56:59], v248, s[28:29] offset:2048
	global_load_dwordx4 v[60:63], v248, s[28:29] offset:3072
	s_add_u32 s28, s28, 0x20000
	s_addc_u32 s29, s29, 0
	s_waitcnt vmcnt(18)
	s_waitcnt lgkmcnt(0)
	v_mfma_f32_16x16x32_bf16 v[8:11], v[64:67], v[96:99], 0
	v_mfma_f32_16x16x32_bf16 v[12:15], v[72:75], v[96:99], 0
	v_mfma_f32_16x16x32_bf16 v[8:11], v[68:71], v[100:103], v[8:11]
	v_mfma_f32_16x16x32_bf16 v[12:15], v[76:79], v[100:103], v[12:15]
	v_cvt_pk_bf16_f32 v112, v0, v1
	v_cvt_pk_bf16_f32 v113, v2, v3
	v_cvt_pk_bf16_f32 v114, v4, v5
	v_cvt_pk_bf16_f32 v115, v6, v7
	global_store_dwordx2 v251, v[112:113], s[40:41]
	global_store_dwordx2 v251, v[114:115], s[40:41] offset:512
	s_add_u32 s40, s40, 0x100000
	s_addc_u32 s41, s41, 0
	s_nop 7
	v_add_f32_e32 v0, v0, v8
	v_add_f32_e32 v1, v1, v9
	v_add_f32_e32 v2, v2, v10
	v_add_f32_e32 v3, v3, v11
	v_add_f32_e32 v4, v4, v12
	v_add_f32_e32 v5, v5, v13
	v_add_f32_e32 v6, v6, v14
	v_add_f32_e32 v7, v7, v15
	v_mul_f32_e32 v0, v0, v104
	v_mul_f32_e32 v1, v1, v105
	v_mul_f32_e32 v2, v2, v106
	v_mul_f32_e32 v3, v3, v107
	v_mul_f32_e32 v4, v4, v108
	v_mul_f32_e32 v5, v5, v109
	v_mul_f32_e32 v6, v6, v110
	v_mul_f32_e32 v7, v7, v111
	s_barrier
; __device__ __forceinline__ unsigned pk2(float lo, float hi) { return pg8::cvt_pk_bf16(lo, hi); }
; template <int NDV>
; __device__ __forceinline__ void ph_g12_strip(Frame& F, int id) {
;     ...
;     for (int c0 = 0; c0 < 128; c0 += 4) {
; #pragma unroll
;         for (int u = 0; u < 4; ++u) {
;             const int cc = c0 + u;
;             unsigned char* slot = (unsigned char*)slot_ptr(F, ci0 + cc, h);
;             f32x4 D[2][NDV];
; #pragma unroll
;             for (int j = 0; j < 2; ++j)
; #pragma unroll
;                 for (int n = 0; n < NDV; ++n) { D[j][n] = (f32x4){0.f, 0.f, 0.f, 0.f};
; #pragma unroll
;                     for (int ks = 0; ks < 2; ++ks) D[j][n] = __builtin_amdgcn_mfma_f32_16x16x32_bf16(rk[u][j][ks], rv[u][n][ks], D[j][n], 0, 0, 0); }
; #pragma unroll
;             for (int j = 0; j < 2; ++j) { const int t = 2 * w + j, qd = t >> 2, c = t & 3; const f32x4 A = rA[u][j];
; #pragma unroll
;                 for (int n = 0; n < NDV; ++n) { const int nn = NDV * sl + n; v2u o; o.x = pk2(S[j][n][0], S[j][n][1]); o.y = pk2(S[j][n][2], S[j][n][3]);
;                     *(v2u*)(slot + (size_t)((nn * 8 + 2 * qd + (c >> 1)) * 64 + 2 * (c & 1) * 16) * 16 + sto) = o;
;                     S[j][n] = (S[j][n] + D[j][n]) * A; } }
;             if (cc + 4 < 128) G12_LOAD(u, cc + 4);
	v_add_u32_e32 v116, s30, v248
	s_add_i32 m0, s42, 0x0
	s_add_u32 s30, s30, s37
	global_load_lds_dwordx4 v116, s[34:35]
	v_add_u32_e32 v116, s31, v248
	s_add_i32 m0, s43, 0x0
	s_add_u32 s31, s31, s38
	global_load_lds_dwordx4 v116, s[34:35]
	v_add_u32_e32 v116, s36, v248
	s_add_i32 m0, s61, 0x0
	s_add_u32 s36, s36, s39
	global_load_lds_dwordx4 v116, s[34:35]
	ds_read_b128 v[80:83], v248 offset:24576
	ds_read_b128 v[84:87], v248 offset:25600
	ds_read_b128 v[88:91], v249 offset:40960
	ds_read_b128 v[92:95], v249 offset:41024
	global_load_dwordx4 v[64:67], v248, s[28:29]
	global_load_dwordx4 v[68:71], v248, s[28:29] offset:1024
	global_load_dwordx4 v[72:75], v248, s[28:29] offset:2048
	global_load_dwordx4 v[76:79], v248, s[28:29] offset:3072
	s_add_u32 s28, s28, 0x20000
	s_addc_u32 s29, s29, 0
	ds_read_b128 v[96:99], v248 offset:26624
	ds_read_b128 v[100:103], v248 offset:27648
	ds_read_b128 v[104:107], v249 offset:41984
	ds_read_b128 v[108:111], v249 offset:42048
	s_waitcnt vmcnt(21)
	s_waitcnt lgkmcnt(4)
	v_mfma_f32_16x16x32_bf16 v[8:11], v[16:19], v[80:83], 0
	v_mfma_f32_16x16x32_bf16 v[12:15], v[24:27], v[80:83], 0
	v_mfma_f32_16x16x32_bf16 v[8:11], v[20:23], v[84:87], v[8:11]
	v_mfma_f32_16x16x32_bf16 v[12:15], v[28:31], v[84:87], v[12:15]
	v_cvt_pk_bf16_f32 v112, v0, v1
	v_cvt_pk_bf16_f32 v113, v2, v3
	v_cvt_pk_bf16_f32 v114, v4, v5
	v_cvt_pk_bf16_f32 v115, v6, v7
	global_store_dwordx2 v251, v[112:113], s[40:41]
	global_store_dwordx2 v251, v[114:115], s[40:41] offset:512
	s_add_u32 s40, s40, 0x100000
	s_addc_u32 s41, s41, 0
	s_nop 7
	v_add_f32_e32 v0, v0, v8
	v_add_f32_e32 v1, v1, v9
	v_add_f32_e32 v2, v2, v10
	v_add_f32_e32 v3, v3, v11
	v_add_f32_e32 v4, v4, v12
	v_add_f32_e32 v5, v5, v13
	v_add_f32_e32 v6, v6, v14
	v_add_f32_e32 v7, v7, v15
	v_mul_f32_e32 v0, v0, v88
	v_mul_f32_e32 v1, v1, v89
	v_mul_f32_e32 v2, v2, v90
	v_mul_f32_e32 v3, v3, v91
	v_mul_f32_e32 v4, v4, v92
	v_mul_f32_e32 v5, v5, v93
	v_mul_f32_e32 v6, v6, v94
	v_mul_f32_e32 v7, v7, v95
	global_load_dwordx4 v[16:19], v248, s[28:29]
	global_load_dwordx4 v[20:23], v248, s[28:29] offset:1024
	global_load_dwordx4 v[24:27], v248, s[28:29] offset:2048
	global_load_dwordx4 v[28:31], v248, s[28:29] offset:3072
	s_add_u32 s28, s28, 0x20000
	s_addc_u32 s29, s29, 0
	ds_read_b128 v[80:83], v248 offset:28672
	ds_read_b128 v[84:87], v248 offset:29696
	ds_read_b128 v[88:91], v249 offset:43008
	ds_read_b128 v[92:95], v249 offset:43072
	s_waitcnt vmcnt(21)
	s_waitcnt lgkmcnt(4)
	v_mfma_f32_16x16x32_bf16 v[8:11], v[32:35], v[96:99], 0
	v_mfma_f32_16x16x32_bf16 v[12:15], v[40:43], v[96:99], 0
	v_mfma_f32_16x16x32_bf16 v[8:11], v[36:39], v[100:103], v[8:11]
	v_mfma_f32_16x16x32_bf16 v[12:15], v[44:47], v[100:103], v[12:15]
	v_cvt_pk_bf16_f32 v112, v0, v1
	v_cvt_pk_bf16_f32 v113, v2, v3
	v_cvt_pk_bf16_f32 v114, v4, v5
	v_cvt_pk_bf16_f32 v115, v6, v7
	global_store_dwordx2 v251, v[112:113], s[40:41]
	global_store_dwordx2 v251, v[114:115], s[40:41] offset:512
	s_add_u32 s40, s40, 0x100000
	s_addc_u32 s41, s41, 0
	s_nop 7
	v_add_f32_e32 v0, v0, v8
	v_add_f32_e32 v1, v1, v9
	v_add_f32_e32 v2, v2, v10
	v_add_f32_e32 v3, v3, v11
	v_add_f32_e32 v4, v4, v12
	v_add_f32_e32 v5, v5, v13
	v_add_f32_e32 v6, v6, v14
	v_add_f32_e32 v7, v7, v15
	v_mul_f32_e32 v0, v0, v104
	v_mul_f32_e32 v1, v1, v105
	v_mul_f32_e32 v2, v2, v106
	v_mul_f32_e32 v3, v3, v107
	v_mul_f32_e32 v4, v4, v108
	v_mul_f32_e32 v5, v5, v109
	v_mul_f32_e32 v6, v6, v110
	v_mul_f32_e32 v7, v7, v111
	global_load_dwordx4 v[32:35], v248, s[28:29]
	global_load_dwordx4 v[36:39], v248, s[28:29] offset:1024
	global_load_dwordx4 v[40:43], v248, s[28:29] offset:2048
	global_load_dwordx4 v[44:47], v248, s[28:29] offset:3072
	s_add_u32 s28, s28, 0x20000
	s_addc_u32 s29, s29, 0
	ds_read_b128 v[96:99], v248 offset:30720
	ds_read_b128 v[100:103], v248 offset:31744
	ds_read_b128 v[104:107], v249 offset:44032
	ds_read_b128 v[108:111], v249 offset:44096
	s_waitcnt vmcnt(21)
	s_waitcnt lgkmcnt(4)
	v_mfma_f32_16x16x32_bf16 v[8:11], v[48:51], v[80:83], 0
	v_mfma_f32_16x16x32_bf16 v[12:15], v[56:59], v[80:83], 0
	v_mfma_f32_16x16x32_bf16 v[8:11], v[52:55], v[84:87], v[8:11]
	v_mfma_f32_16x16x32_bf16 v[12:15], v[60:63], v[84:87], v[12:15]
	v_cvt_pk_bf16_f32 v112, v0, v1
	v_cvt_pk_bf16_f32 v113, v2, v3
	v_cvt_pk_bf16_f32 v114, v4, v5
	v_cvt_pk_bf16_f32 v115, v6, v7
	global_store_dwordx2 v251, v[112:113], s[40:41]
	global_store_dwordx2 v251, v[114:115], s[40:41] offset:512
	s_add_u32 s40, s40, 0x100000
	s_addc_u32 s41, s41, 0
	s_nop 7
	v_add_f32_e32 v0, v0, v8
	v_add_f32_e32 v1, v1, v9
	v_add_f32_e32 v2, v2, v10
	v_add_f32_e32 v3, v3, v11
	v_add_f32_e32 v4, v4, v12
	v_add_f32_e32 v5, v5, v13
	v_add_f32_e32 v6, v6, v14
	v_add_f32_e32 v7, v7, v15
	v_mul_f32_e32 v0, v0, v88
	v_mul_f32_e32 v1, v1, v89
	v_mul_f32_e32 v2, v2, v90
	v_mul_f32_e32 v3, v3, v91
	v_mul_f32_e32 v4, v4, v92
	v_mul_f32_e32 v5, v5, v93
	v_mul_f32_e32 v6, v6, v94
	v_mul_f32_e32 v7, v7, v95
	global_load_dwordx4 v[48:51], v248, s[28:29]
	global_load_dwordx4 v[52:55], v248, s[28:29] offset:1024
	global_load_dwordx4 v[56:59], v248, s[28:29] offset:2048
	global_load_dwordx4 v[60:63], v248, s[28:29] offset:3072
	s_add_u32 s28, s28, 0x20000
	s_addc_u32 s29, s29, 0
	ds_read_b128 v[80:83], v248 offset:32768
	ds_read_b128 v[84:87], v248 offset:33792
	ds_read_b128 v[88:91], v249 offset:45056
	ds_read_b128 v[92:95], v249 offset:45120
	s_waitcnt vmcnt(18)
	s_waitcnt lgkmcnt(4)
; __device__ __forceinline__ unsigned pk2(float lo, float hi) { return pg8::cvt_pk_bf16(lo, hi); }
; template <int NDV>
; __device__ __forceinline__ void ph_g12_strip(Frame& F, int id) {
;     ...
;     for (int c0 = 0; c0 < 128; c0 += 4) {
; #pragma unroll
;         for (int u = 0; u < 4; ++u) {
;             const int cc = c0 + u;
;             unsigned char* slot = (unsigned char*)slot_ptr(F, ci0 + cc, h);
;             f32x4 D[2][NDV];
; #pragma unroll
;             for (int j = 0; j < 2; ++j)
; #pragma unroll
;                 for (int n = 0; n < NDV; ++n) { D[j][n] = (f32x4){0.f, 0.f, 0.f, 0.f};
; #pragma unroll
;                     for (int ks = 0; ks < 2; ++ks) D[j][n] = __builtin_amdgcn_mfma_f32_16x16x32_bf16(rk[u][j][ks], rv[u][n][ks], D[j][n], 0, 0, 0); }
; #pragma unroll
;             for (int j = 0; j < 2; ++j) { const int t = 2 * w + j, qd = t >> 2, c = t & 3; const f32x4 A = rA[u][j];
; #pragma unroll
;                 for (int n = 0; n < NDV; ++n) { const int nn = NDV * sl + n; v2u o; o.x = pk2(S[j][n][0], S[j][n][1]); o.y = pk2(S[j][n][2], S[j][n][3]);
;                     *(v2u*)(slot + (size_t)((nn * 8 + 2 * qd + (c >> 1)) * 64 + 2 * (c & 1) * 16) * 16 + sto) = o;
;                     S[j][n] = (S[j][n] + D[j][n]) * A; } }
;             if (cc + 4 < 128) G12_LOAD(u, cc + 4);
	v_mfma_f32_16x16x32_bf16 v[8:11], v[64:67], v[96:99], 0
	v_mfma_f32_16x16x32_bf16 v[12:15], v[72:75], v[96:99], 0
	v_mfma_f32_16x16x32_bf16 v[8:11], v[68:71], v[100:103], v[8:11]
	v_mfma_f32_16x16x32_bf16 v[12:15], v[76:79], v[100:103], v[12:15]
	v_cvt_pk_bf16_f32 v112, v0, v1
	v_cvt_pk_bf16_f32 v113, v2, v3
	v_cvt_pk_bf16_f32 v114, v4, v5
	v_cvt_pk_bf16_f32 v115, v6, v7
	global_store_dwordx2 v251, v[112:113], s[40:41]
	global_store_dwordx2 v251, v[114:115], s[40:41] offset:512
	s_add_u32 s40, s40, 0x100000
	s_addc_u32 s41, s41, 0
	s_nop 7
	v_add_f32_e32 v0, v0, v8
	v_add_f32_e32 v1, v1, v9
	v_add_f32_e32 v2, v2, v10
	v_add_f32_e32 v3, v3, v11
	v_add_f32_e32 v4, v4, v12
	v_add_f32_e32 v5, v5, v13
	v_add_f32_e32 v6, v6, v14
	v_add_f32_e32 v7, v7, v15
	v_mul_f32_e32 v0, v0, v104
	v_mul_f32_e32 v1, v1, v105
	v_mul_f32_e32 v2, v2, v106
	v_mul_f32_e32 v3, v3, v107
	v_mul_f32_e32 v4, v4, v108
	v_mul_f32_e32 v5, v5, v109
	v_mul_f32_e32 v6, v6, v110
	v_mul_f32_e32 v7, v7, v111
	global_load_dwordx4 v[64:67], v248, s[28:29]
	global_load_dwordx4 v[68:71], v248, s[28:29] offset:1024
	global_load_dwordx4 v[72:75], v248, s[28:29] offset:2048
	global_load_dwordx4 v[76:79], v248, s[28:29] offset:3072
	s_add_u32 s28, s28, 0x20000
	s_addc_u32 s29, s29, 0
	ds_read_b128 v[96:99], v248 offset:34816
	ds_read_b128 v[100:103], v248 offset:35840
	ds_read_b128 v[104:107], v249 offset:46080
	ds_read_b128 v[108:111], v249 offset:46144
	s_waitcnt vmcnt(18)
	s_waitcnt lgkmcnt(4)
	v_mfma_f32_16x16x32_bf16 v[8:11], v[16:19], v[80:83], 0
	v_mfma_f32_16x16x32_bf16 v[12:15], v[24:27], v[80:83], 0
	v_mfma_f32_16x16x32_bf16 v[8:11], v[20:23], v[84:87], v[8:11]
	v_mfma_f32_16x16x32_bf16 v[12:15], v[28:31], v[84:87], v[12:15]
	v_cvt_pk_bf16_f32 v112, v0, v1
	v_cvt_pk_bf16_f32 v113, v2, v3
	v_cvt_pk_bf16_f32 v114, v4, v5
	v_cvt_pk_bf16_f32 v115, v6, v7
	global_store_dwordx2 v251, v[112:113], s[40:41]
	global_store_dwordx2 v251, v[114:115], s[40:41] offset:512
	s_add_u32 s40, s40, 0x100000
	s_addc_u32 s41, s41, 0
	s_nop 7
	v_add_f32_e32 v0, v0, v8
	v_add_f32_e32 v1, v1, v9
	v_add_f32_e32 v2, v2, v10
	v_add_f32_e32 v3, v3, v11
	v_add_f32_e32 v4, v4, v12
	v_add_f32_e32 v5, v5, v13
	v_add_f32_e32 v6, v6, v14
	v_add_f32_e32 v7, v7, v15
	v_mul_f32_e32 v0, v0, v88
	v_mul_f32_e32 v1, v1, v89
	v_mul_f32_e32 v2, v2, v90
	v_mul_f32_e32 v3, v3, v91
	v_mul_f32_e32 v4, v4, v92
	v_mul_f32_e32 v5, v5, v93
	v_mul_f32_e32 v6, v6, v94
	v_mul_f32_e32 v7, v7, v95
	global_load_dwordx4 v[16:19], v248, s[28:29]
	global_load_dwordx4 v[20:23], v248, s[28:29] offset:1024
	global_load_dwordx4 v[24:27], v248, s[28:29] offset:2048
	global_load_dwordx4 v[28:31], v248, s[28:29] offset:3072
	s_add_u32 s28, s28, 0x20000
	s_addc_u32 s29, s29, 0
	ds_read_b128 v[80:83], v248 offset:36864
	ds_read_b128 v[84:87], v248 offset:37888
	ds_read_b128 v[88:91], v249 offset:47104
	ds_read_b128 v[92:95], v249 offset:47168
	s_waitcnt vmcnt(18)
	s_waitcnt lgkmcnt(4)
	v_mfma_f32_16x16x32_bf16 v[8:11], v[32:35], v[96:99], 0
	v_mfma_f32_16x16x32_bf16 v[12:15], v[40:43], v[96:99], 0
	v_mfma_f32_16x16x32_bf16 v[8:11], v[36:39], v[100:103], v[8:11]
	v_mfma_f32_16x16x32_bf16 v[12:15], v[44:47], v[100:103], v[12:15]
	v_cvt_pk_bf16_f32 v112, v0, v1
	v_cvt_pk_bf16_f32 v113, v2, v3
	v_cvt_pk_bf16_f32 v114, v4, v5
	v_cvt_pk_bf16_f32 v115, v6, v7
	global_store_dwordx2 v251, v[112:113], s[40:41]
	global_store_dwordx2 v251, v[114:115], s[40:41] offset:512
	s_add_u32 s40, s40, 0x100000
	s_addc_u32 s41, s41, 0
	s_nop 7
	v_add_f32_e32 v0, v0, v8
	v_add_f32_e32 v1, v1, v9
	v_add_f32_e32 v2, v2, v10
	v_add_f32_e32 v3, v3, v11
	v_add_f32_e32 v4, v4, v12
	v_add_f32_e32 v5, v5, v13
	v_add_f32_e32 v6, v6, v14
	v_add_f32_e32 v7, v7, v15
	v_mul_f32_e32 v0, v0, v104
	v_mul_f32_e32 v1, v1, v105
	v_mul_f32_e32 v2, v2, v106
	v_mul_f32_e32 v3, v3, v107
	v_mul_f32_e32 v4, v4, v108
	v_mul_f32_e32 v5, v5, v109
	v_mul_f32_e32 v6, v6, v110
	v_mul_f32_e32 v7, v7, v111
	global_load_dwordx4 v[32:35], v248, s[28:29]
	global_load_dwordx4 v[36:39], v248, s[28:29] offset:1024
	global_load_dwordx4 v[40:43], v248, s[28:29] offset:2048
	global_load_dwordx4 v[44:47], v248, s[28:29] offset:3072
	s_add_u32 s28, s28, 0x20000
	s_addc_u32 s29, s29, 0
	ds_read_b128 v[96:99], v248 offset:38912
	ds_read_b128 v[100:103], v248 offset:39936
	ds_read_b128 v[104:107], v249 offset:48128
	ds_read_b128 v[108:111], v249 offset:48192
	s_waitcnt vmcnt(18)
	s_waitcnt lgkmcnt(4)
	v_mfma_f32_16x16x32_bf16 v[8:11], v[48:51], v[80:83], 0
	v_mfma_f32_16x16x32_bf16 v[12:15], v[56:59], v[80:83], 0
	v_mfma_f32_16x16x32_bf16 v[8:11], v[52:55], v[84:87], v[8:11]
	v_mfma_f32_16x16x32_bf16 v[12:15], v[60:63], v[84:87], v[12:15]
	v_cvt_pk_bf16_f32 v112, v0, v1
	v_cvt_pk_bf16_f32 v113, v2, v3
	v_cvt_pk_bf16_f32 v114, v4, v5
	v_cvt_pk_bf16_f32 v115, v6, v7
	global_store_dwordx2 v251, v[112:113], s[40:41]
	global_store_dwordx2 v251, v[114:115], s[40:41] offset:512
	s_add_u32 s40, s40, 0x100000
	s_addc_u32 s41, s41, 0
	s_nop 7
	v_add_f32_e32 v0, v0, v8
	v_add_f32_e32 v1, v1, v9
	v_add_f32_e32 v2, v2, v10
	v_add_f32_e32 v3, v3, v11
	v_add_f32_e32 v4, v4, v12
	v_add_f32_e32 v5, v5, v13
	v_add_f32_e32 v6, v6, v14
	v_add_f32_e32 v7, v7, v15
	v_mul_f32_e32 v0, v0, v88
	v_mul_f32_e32 v1, v1, v89
	v_mul_f32_e32 v2, v2, v90
	v_mul_f32_e32 v3, v3, v91
	v_mul_f32_e32 v4, v4, v92
	v_mul_f32_e32 v5, v5, v93
	v_mul_f32_e32 v6, v6, v94
	v_mul_f32_e32 v7, v7, v95
	global_load_dwordx4 v[48:51], v248, s[28:29]
	global_load_dwordx4 v[52:55], v248, s[28:29] offset:1024
	global_load_dwordx4 v[56:59], v248, s[28:29] offset:2048
	global_load_dwordx4 v[60:63], v248, s[28:29] offset:3072
	s_add_u32 s28, s28, 0x20000
	s_addc_u32 s29, s29, 0
	s_waitcnt vmcnt(18)
	s_waitcnt lgkmcnt(0)
	v_mfma_f32_16x16x32_bf16 v[8:11], v[64:67], v[96:99], 0
	v_mfma_f32_16x16x32_bf16 v[12:15], v[72:75], v[96:99], 0
	v_mfma_f32_16x16x32_bf16 v[8:11], v[68:71], v[100:103], v[8:11]
	v_mfma_f32_16x16x32_bf16 v[12:15], v[76:79], v[100:103], v[12:15]
	v_cvt_pk_bf16_f32 v112, v0, v1
	v_cvt_pk_bf16_f32 v113, v2, v3
	v_cvt_pk_bf16_f32 v114, v4, v5
	v_cvt_pk_bf16_f32 v115, v6, v7
	global_store_dwordx2 v251, v[112:113], s[40:41]
	global_store_dwordx2 v251, v[114:115], s[40:41] offset:512
	s_add_u32 s40, s40, 0x100000
	s_addc_u32 s41, s41, 0
	s_nop 7
	v_add_f32_e32 v0, v0, v8
	v_add_f32_e32 v1, v1, v9
	v_add_f32_e32 v2, v2, v10
	v_add_f32_e32 v3, v3, v11
	v_add_f32_e32 v4, v4, v12
	v_add_f32_e32 v5, v5, v13
	v_add_f32_e32 v6, v6, v14
	v_add_f32_e32 v7, v7, v15
	v_mul_f32_e32 v0, v0, v104
	v_mul_f32_e32 v1, v1, v105
	v_mul_f32_e32 v2, v2, v106
	v_mul_f32_e32 v3, v3, v107
	v_mul_f32_e32 v4, v4, v108
	v_mul_f32_e32 v5, v5, v109
	v_mul_f32_e32 v6, v6, v110
	v_mul_f32_e32 v7, v7, v111
	s_sub_i32 s8, s8, 1
	s_cmp_lg_u32 s8, 0
	s_cbranch_scc1 .Lstrip2_loop
; template <int NDV>
; __device__ __forceinline__ void ph_g12_strip(Frame& F, int id) {
;     ...
; #pragma unroll
;     for (int j = 0; j < 2; ++j)
; #pragma unroll
;         for (int n = 0; n < NDV; ++n) { float* op = F.out + O_SGP + ((size_t)((seq * NH + h) * DK + 16 * (2 * w + j) + 4 * fq)) * DV + 16 * (NDV * sl + n) + fr;
; #pragma unroll
;             for (int i = 0; i < 4; ++i) op[(size_t)i * DV] = S[j][n][i]; }
	s_waitcnt vmcnt(0) lgkmcnt(0)
	s_barrier
	s_lshl_b32 s0, s58, 2
	s_add_u32 s0, s0, s59
	s_lshl_b32 s0, s0, 19
	s_lshl_b32 s1, s79, 16
	s_add_u32 s0, s0, s1
	s_lshl_b32 s1, s60, 6
	s_add_u32 s0, s0, s1
	s_add_u32 s0, s0, 0x12000000
	s_add_u32 s0, s70, s0
	s_addc_u32 s1, s71, 0
	v_and_b32_e32 v116, 15, v166
	v_lshrrev_b32_e32 v117, 4, v166
	v_lshlrev_b32_e32 v116, 2, v116
	v_lshl_add_u32 v116, v117, 13, v116
	v_add_u32_e32 v117, 0x1000, v116
	global_store_dword v116, v0, s[0:1]
	global_store_dword v116, v1, s[0:1] offset:2048
	global_store_dword v117, v2, s[0:1]
	global_store_dword v117, v3, s[0:1] offset:2048
	s_add_u32 s0, s0, 0x8000
	s_addc_u32 s1, s1, 0
	global_store_dword v116, v4, s[0:1]
	global_store_dword v116, v5, s[0:1] offset:2048
	global_store_dword v117, v6, s[0:1]
	global_store_dword v117, v7, s[0:1] offset:2048
	s_branch .LBB0_474
